# GEMM K-loops: one static priority raise for waves 4-7 before each K-loop instead of per-segment flips (vcc temp); R7_CA/R7_CB static raises
# baseline (speedup 1.0000x reference)
; template <class Epi>
; __device__ __forceinline__ void gemm_phase(PG8_LAS unsigned char* lds, const Gemm g, const StaticOrder& S, const Epi& E) {
;     ...
;     const bool has_next = S.next(ui + 1, nxt);
;     const char* nA = has_next ? (const char*)g.A + (size_t)nxt.pm * tstep : cA; const char* nB = has_next ? (const char*)g.Bt + (size_t)nxt.pn * tstep : cB;
;     ...
; #pragma unroll
;     for (int a = 0; a < 2; ++a)
; #pragma unroll
;       for (int b = 0; b < 2; ++b)
; #pragma unroll
;         for (int m = 0; m < 4; ++m)
; #pragma unroll
;           for (int n = 0; n < 2; ++n) acc[a][b][m][n] = (f32x4){0.f, 0.f, 0.f, 0.f};
;     cur = nxt; cA = nA; cB = nB; ++ui;
.LBB0_33:
	s_ashr_i32 s11, s10, 31
	v_cmp_lt_i64_e32 vcc, s[30:31], v[132:133]
	s_lshl_b64 s[30:31], s[10:11], 19
	s_add_u32 s30, s88, s30
	s_addc_u32 s31, s89, s31
	s_and_b64 s[44:45], vcc, exec
	s_cselect_b32 s11, s31, s49
	s_cselect_b32 s43, s30, s48
	s_ashr_i32 s9, s8, 31
	s_lshl_b64 s[44:45], s[8:9], 19
	v_readlane_b32 s9, v251, 6
	s_add_u32 s44, s9, s44
	v_readlane_b32 s9, v251, 7
	s_addc_u32 s45, s9, s45
	s_and_b64 s[52:53], vcc, exec
	s_cselect_b32 s9, s45, s51
	s_cselect_b32 s47, s44, s50
	s_add_u32 s63, s50, 0x100
	v_mov_b32_e32 v2, 0
	s_addc_u32 s64, s51, 0
	s_mov_b32 s65, -2
	v_mov_b32_e32 v3, v2
	v_mov_b32_e32 v4, v2
	v_mov_b32_e32 v5, v2
	v_mov_b32_e32 v6, v2
	v_mov_b32_e32 v7, v2
	v_mov_b32_e32 v8, v2
	v_mov_b32_e32 v9, v2
	v_mov_b32_e32 v18, v2
	v_mov_b32_e32 v19, v2
	v_mov_b32_e32 v20, v2
	v_mov_b32_e32 v21, v2
	v_mov_b32_e32 v22, v2
	v_mov_b32_e32 v23, v2
	v_mov_b32_e32 v24, v2
	v_mov_b32_e32 v25, v2
	v_mov_b32_e32 v34, v2
	v_mov_b32_e32 v35, v2
	v_mov_b32_e32 v36, v2
	v_mov_b32_e32 v37, v2
	v_mov_b32_e32 v38, v2
	v_mov_b32_e32 v39, v2
	v_mov_b32_e32 v40, v2
	v_mov_b32_e32 v41, v2
	v_mov_b32_e32 v50, v2
	v_mov_b32_e32 v51, v2
	v_mov_b32_e32 v52, v2
	v_mov_b32_e32 v53, v2
	v_mov_b32_e32 v54, v2
	v_mov_b32_e32 v55, v2
	v_mov_b32_e32 v56, v2
	v_mov_b32_e32 v57, v2
	v_mov_b32_e32 v10, v2
	v_mov_b32_e32 v11, v2
	v_mov_b32_e32 v12, v2
	v_mov_b32_e32 v13, v2
	v_mov_b32_e32 v14, v2
	v_mov_b32_e32 v15, v2
	v_mov_b32_e32 v16, v2
	v_mov_b32_e32 v17, v2
	v_mov_b32_e32 v26, v2
	v_mov_b32_e32 v27, v2
	v_mov_b32_e32 v28, v2
	v_mov_b32_e32 v29, v2
	v_mov_b32_e32 v30, v2
	v_mov_b32_e32 v31, v2
	v_mov_b32_e32 v32, v2
	v_mov_b32_e32 v33, v2
	v_mov_b32_e32 v42, v2
	v_mov_b32_e32 v43, v2
	v_mov_b32_e32 v44, v2
	v_mov_b32_e32 v45, v2
	v_mov_b32_e32 v46, v2
	v_mov_b32_e32 v47, v2
	v_mov_b32_e32 v48, v2
	v_mov_b32_e32 v49, v2
	v_mov_b32_e32 v58, v2
	v_mov_b32_e32 v59, v2
	v_mov_b32_e32 v60, v2
	v_mov_b32_e32 v61, v2
	v_mov_b32_e32 v62, v2
	v_mov_b32_e32 v63, v2
	v_mov_b32_e32 v64, v2
	v_mov_b32_e32 v65, v2
	v_mov_b32_e32 v66, v2
	v_mov_b32_e32 v67, v2
	v_mov_b32_e32 v68, v2
	v_mov_b32_e32 v69, v2
	v_mov_b32_e32 v70, v2
	v_mov_b32_e32 v71, v2
	v_mov_b32_e32 v72, v2
	v_mov_b32_e32 v73, v2
	v_mov_b32_e32 v82, v2
	v_mov_b32_e32 v83, v2
	v_mov_b32_e32 v84, v2
	v_mov_b32_e32 v85, v2
	v_mov_b32_e32 v86, v2
	v_mov_b32_e32 v87, v2
	v_mov_b32_e32 v88, v2
	v_mov_b32_e32 v89, v2
	v_mov_b32_e32 v98, v2
	v_mov_b32_e32 v99, v2
	v_mov_b32_e32 v100, v2
	v_mov_b32_e32 v101, v2
	v_mov_b32_e32 v102, v2
	v_mov_b32_e32 v103, v2
	v_mov_b32_e32 v104, v2
	v_mov_b32_e32 v105, v2
	v_mov_b32_e32 v114, v2
	v_mov_b32_e32 v115, v2
	v_mov_b32_e32 v116, v2
	v_mov_b32_e32 v117, v2
	v_mov_b32_e32 v118, v2
	v_mov_b32_e32 v119, v2
	v_mov_b32_e32 v120, v2
	v_mov_b32_e32 v121, v2
	v_mov_b32_e32 v74, v2
	v_mov_b32_e32 v75, v2
	v_mov_b32_e32 v76, v2
	v_mov_b32_e32 v77, v2
	v_mov_b32_e32 v78, v2
	v_mov_b32_e32 v79, v2
	v_mov_b32_e32 v80, v2
	v_mov_b32_e32 v81, v2
	v_mov_b32_e32 v90, v2
	v_mov_b32_e32 v91, v2
	v_mov_b32_e32 v92, v2
	v_mov_b32_e32 v93, v2
	v_mov_b32_e32 v94, v2
	v_mov_b32_e32 v95, v2
	v_mov_b32_e32 v96, v2
	v_mov_b32_e32 v97, v2
	v_mov_b32_e32 v106, v2
	v_mov_b32_e32 v107, v2
	v_mov_b32_e32 v108, v2
	v_mov_b32_e32 v109, v2
	v_mov_b32_e32 v110, v2
	v_mov_b32_e32 v111, v2
	v_mov_b32_e32 v112, v2
	v_mov_b32_e32 v113, v2
	v_mov_b32_e32 v122, v2
	v_mov_b32_e32 v123, v2
	v_mov_b32_e32 v124, v2
	v_mov_b32_e32 v125, v2
	v_mov_b32_e32 v126, v2
	v_mov_b32_e32 v127, v2
	v_mov_b32_e32 v128, v2
	v_mov_b32_e32 v129, v2
	v_readfirstlane_b32 vcc_lo, v168
	s_lshr_b32 vcc_lo, vcc_lo, 6
	s_cmp_ge_u32 vcc_lo, 4
	s_cbranch_scc0 .Lgp_0
	s_setprio 1

; template <class Epi>
; __device__ __forceinline__ void gemm_phase(PG8_LAS unsigned char* lds, const Gemm g, const StaticOrder& S, const Epi& E) {
;     ...
;     const bool has_next = S.next(ui + 1, nxt);
;     const char* nA = has_next ? (const char*)g.A + (size_t)nxt.pm * tstep : cA; const char* nB = has_next ? (const char*)g.Bt + (size_t)nxt.pn * tstep : cB;
;     ...
; #pragma unroll
;     for (int a = 0; a < 2; ++a)
; #pragma unroll
;       for (int b = 0; b < 2; ++b)
; #pragma unroll
;         for (int m = 0; m < 4; ++m)
; #pragma unroll
;           for (int n = 0; n < 2; ++n) acc[a][b][m][n] = (f32x4){0.f, 0.f, 0.f, 0.f};
;     cur = nxt; cA = nA; cB = nB; ++ui;
.LBB0_293:
	s_ashr_i32 s51, s50, 31
	v_cmp_lt_i64_e32 vcc, s[44:45], v[136:137]
	s_lshl_b64 s[44:45], s[50:51], 20
	s_add_u32 s52, s24, s44
	s_addc_u32 s53, s25, s45
	s_and_b64 s[44:45], vcc, exec
	s_cselect_b32 s7, s53, s11
	s_cselect_b32 s9, s52, s10
	s_ashr_i32 s31, s30, 31
	s_lshl_b64 s[44:45], s[30:31], 20
	s_add_u32 s54, s22, s44
	s_addc_u32 s55, s23, s45
	s_and_b64 s[44:45], vcc, exec
	s_cselect_b32 s31, s55, s43
	s_cselect_b32 s46, s54, s42
	s_add_u32 s10, s10, 0x80080
	s_addc_u32 s11, s11, 0
	s_add_u32 s47, s42, 0x100
	v_mov_b32_e32 v2, 0
	s_addc_u32 s48, s43, 0
	s_mov_b32 s49, -2
	v_mov_b32_e32 v3, v2
	v_mov_b32_e32 v4, v2
	v_mov_b32_e32 v5, v2
	v_mov_b32_e32 v6, v2
	v_mov_b32_e32 v7, v2
	v_mov_b32_e32 v8, v2
	v_mov_b32_e32 v9, v2
	v_mov_b32_e32 v18, v2
	v_mov_b32_e32 v19, v2
	v_mov_b32_e32 v20, v2
	v_mov_b32_e32 v21, v2
	v_mov_b32_e32 v22, v2
	v_mov_b32_e32 v23, v2
	v_mov_b32_e32 v24, v2
	v_mov_b32_e32 v25, v2
	v_mov_b32_e32 v34, v2
	v_mov_b32_e32 v35, v2
	v_mov_b32_e32 v36, v2
	v_mov_b32_e32 v37, v2
	v_mov_b32_e32 v38, v2
	v_mov_b32_e32 v39, v2
	v_mov_b32_e32 v40, v2
	v_mov_b32_e32 v41, v2
	v_mov_b32_e32 v50, v2
	v_mov_b32_e32 v51, v2
	v_mov_b32_e32 v52, v2
	v_mov_b32_e32 v53, v2
	v_mov_b32_e32 v54, v2
	v_mov_b32_e32 v55, v2
	v_mov_b32_e32 v56, v2
	v_mov_b32_e32 v57, v2
	v_mov_b32_e32 v10, v2
	v_mov_b32_e32 v11, v2
	v_mov_b32_e32 v12, v2
	v_mov_b32_e32 v13, v2
	v_mov_b32_e32 v14, v2
	v_mov_b32_e32 v15, v2
	v_mov_b32_e32 v16, v2
	v_mov_b32_e32 v17, v2
	v_mov_b32_e32 v26, v2
	v_mov_b32_e32 v27, v2
	v_mov_b32_e32 v28, v2
	v_mov_b32_e32 v29, v2
	v_mov_b32_e32 v30, v2
	v_mov_b32_e32 v31, v2
	v_mov_b32_e32 v32, v2
	v_mov_b32_e32 v33, v2
	v_mov_b32_e32 v42, v2
	v_mov_b32_e32 v43, v2
	v_mov_b32_e32 v44, v2
	v_mov_b32_e32 v45, v2
	v_mov_b32_e32 v46, v2
	v_mov_b32_e32 v47, v2
	v_mov_b32_e32 v48, v2
	v_mov_b32_e32 v49, v2
	v_mov_b32_e32 v58, v2
	v_mov_b32_e32 v59, v2
	v_mov_b32_e32 v60, v2
	v_mov_b32_e32 v61, v2
	v_mov_b32_e32 v62, v2
	v_mov_b32_e32 v63, v2
	v_mov_b32_e32 v64, v2
	v_mov_b32_e32 v65, v2
	v_mov_b32_e32 v66, v2
	v_mov_b32_e32 v67, v2
	v_mov_b32_e32 v68, v2
	v_mov_b32_e32 v69, v2
	v_mov_b32_e32 v70, v2
	v_mov_b32_e32 v71, v2
	v_mov_b32_e32 v72, v2
	v_mov_b32_e32 v73, v2
	v_mov_b32_e32 v82, v2
	v_mov_b32_e32 v83, v2
	v_mov_b32_e32 v84, v2
	v_mov_b32_e32 v85, v2
	v_mov_b32_e32 v86, v2
	v_mov_b32_e32 v87, v2
	v_mov_b32_e32 v88, v2
	v_mov_b32_e32 v89, v2
	v_mov_b32_e32 v98, v2
	v_mov_b32_e32 v99, v2
	v_mov_b32_e32 v100, v2
	v_mov_b32_e32 v101, v2
	v_mov_b32_e32 v102, v2
	v_mov_b32_e32 v103, v2
	v_mov_b32_e32 v104, v2
	v_mov_b32_e32 v105, v2
	v_mov_b32_e32 v114, v2
	v_mov_b32_e32 v115, v2
	v_mov_b32_e32 v116, v2
	v_mov_b32_e32 v117, v2
	v_mov_b32_e32 v118, v2
	v_mov_b32_e32 v119, v2
	v_mov_b32_e32 v120, v2
	v_mov_b32_e32 v121, v2
	v_mov_b32_e32 v74, v2
	v_mov_b32_e32 v75, v2
	v_mov_b32_e32 v76, v2
	v_mov_b32_e32 v77, v2
	v_mov_b32_e32 v78, v2
	v_mov_b32_e32 v79, v2
	v_mov_b32_e32 v80, v2
	v_mov_b32_e32 v81, v2
	v_mov_b32_e32 v90, v2
	v_mov_b32_e32 v91, v2
	v_mov_b32_e32 v92, v2
	v_mov_b32_e32 v93, v2
	v_mov_b32_e32 v94, v2
	v_mov_b32_e32 v95, v2
	v_mov_b32_e32 v96, v2
	v_mov_b32_e32 v97, v2
	v_mov_b32_e32 v106, v2
	v_mov_b32_e32 v107, v2
	v_mov_b32_e32 v108, v2
	v_mov_b32_e32 v109, v2
	v_mov_b32_e32 v110, v2
	v_mov_b32_e32 v111, v2
	v_mov_b32_e32 v112, v2
	v_mov_b32_e32 v113, v2
	v_mov_b32_e32 v122, v2
	v_mov_b32_e32 v123, v2
	v_mov_b32_e32 v124, v2
	v_mov_b32_e32 v125, v2
	v_mov_b32_e32 v126, v2
	v_mov_b32_e32 v127, v2
	v_mov_b32_e32 v128, v2
	v_mov_b32_e32 v129, v2
	v_readfirstlane_b32 vcc_lo, v168
	s_lshr_b32 vcc_lo, vcc_lo, 6
	s_cmp_ge_u32 vcc_lo, 4
	s_cbranch_scc0 .Lgp_1
	s_setprio 1

; template <class Epi>
; __device__ __forceinline__ void gemm_phase(PG8_LAS unsigned char* lds, const Gemm g, const StaticOrder& S, const Epi& E) {
;     ...
;     const bool has_next = S.next(ui + 1, nxt);
;     const char* nA = has_next ? (const char*)g.A + (size_t)nxt.pm * tstep : cA; const char* nB = has_next ? (const char*)g.Bt + (size_t)nxt.pn * tstep : cB;
;     ...
; #pragma unroll
;     for (int a = 0; a < 2; ++a)
; #pragma unroll
;       for (int b = 0; b < 2; ++b)
; #pragma unroll
;         for (int m = 0; m < 4; ++m)
; #pragma unroll
;           for (int n = 0; n < 2; ++n) acc[a][b][m][n] = (f32x4){0.f, 0.f, 0.f, 0.f};
;     cur = nxt; cA = nA; cB = nB; ++ui;
.LBB0_1045:
	s_ashr_i32 s11, s10, 31
	v_cmp_lt_i64_e32 vcc, s[30:31], v[132:133]
	s_lshl_b64 s[30:31], s[10:11], 20
	s_add_u32 s30, s90, s30
	s_addc_u32 s31, s91, s31
	s_and_b64 s[44:45], vcc, exec
	s_cselect_b32 s11, s31, s49
	s_cselect_b32 s43, s30, s48
	s_ashr_i32 s9, s8, 31
	s_lshl_b64 s[44:45], s[8:9], 20
	v_readlane_b32 s9, v251, 33
	s_add_u32 s44, s9, s44
	v_readlane_b32 s9, v251, 34
	s_addc_u32 s45, s9, s45
	s_and_b64 s[52:53], vcc, exec
	s_cselect_b32 s9, s45, s51
	s_cselect_b32 s47, s44, s50
	s_add_u32 s63, s50, 0x100
	v_mov_b32_e32 v2, 0
	s_addc_u32 s64, s51, 0
	s_mov_b32 s65, -2
	v_mov_b32_e32 v3, v2
	v_mov_b32_e32 v4, v2
	v_mov_b32_e32 v5, v2
	v_mov_b32_e32 v6, v2
	v_mov_b32_e32 v7, v2
	v_mov_b32_e32 v8, v2
	v_mov_b32_e32 v9, v2
	v_mov_b32_e32 v18, v2
	v_mov_b32_e32 v19, v2
	v_mov_b32_e32 v20, v2
	v_mov_b32_e32 v21, v2
	v_mov_b32_e32 v22, v2
	v_mov_b32_e32 v23, v2
	v_mov_b32_e32 v24, v2
	v_mov_b32_e32 v25, v2
	v_mov_b32_e32 v34, v2
	v_mov_b32_e32 v35, v2
	v_mov_b32_e32 v36, v2
	v_mov_b32_e32 v37, v2
	v_mov_b32_e32 v38, v2
	v_mov_b32_e32 v39, v2
	v_mov_b32_e32 v40, v2
	v_mov_b32_e32 v41, v2
	v_mov_b32_e32 v50, v2
	v_mov_b32_e32 v51, v2
	v_mov_b32_e32 v52, v2
	v_mov_b32_e32 v53, v2
	v_mov_b32_e32 v54, v2
	v_mov_b32_e32 v55, v2
	v_mov_b32_e32 v56, v2
	v_mov_b32_e32 v57, v2
	v_mov_b32_e32 v10, v2
	v_mov_b32_e32 v11, v2
	v_mov_b32_e32 v12, v2
	v_mov_b32_e32 v13, v2
	v_mov_b32_e32 v14, v2
	v_mov_b32_e32 v15, v2
	v_mov_b32_e32 v16, v2
	v_mov_b32_e32 v17, v2
	v_mov_b32_e32 v26, v2
	v_mov_b32_e32 v27, v2
	v_mov_b32_e32 v28, v2
	v_mov_b32_e32 v29, v2
	v_mov_b32_e32 v30, v2
	v_mov_b32_e32 v31, v2
	v_mov_b32_e32 v32, v2
	v_mov_b32_e32 v33, v2
	v_mov_b32_e32 v42, v2
	v_mov_b32_e32 v43, v2
	v_mov_b32_e32 v44, v2
	v_mov_b32_e32 v45, v2
	v_mov_b32_e32 v46, v2
	v_mov_b32_e32 v47, v2
	v_mov_b32_e32 v48, v2
	v_mov_b32_e32 v49, v2
	v_mov_b32_e32 v58, v2
	v_mov_b32_e32 v59, v2
	v_mov_b32_e32 v60, v2
	v_mov_b32_e32 v61, v2
	v_mov_b32_e32 v62, v2
	v_mov_b32_e32 v63, v2
	v_mov_b32_e32 v64, v2
	v_mov_b32_e32 v65, v2
	v_mov_b32_e32 v66, v2
	v_mov_b32_e32 v67, v2
	v_mov_b32_e32 v68, v2
	v_mov_b32_e32 v69, v2
	v_mov_b32_e32 v70, v2
	v_mov_b32_e32 v71, v2
	v_mov_b32_e32 v72, v2
	v_mov_b32_e32 v73, v2
	v_mov_b32_e32 v82, v2
	v_mov_b32_e32 v83, v2
	v_mov_b32_e32 v84, v2
	v_mov_b32_e32 v85, v2
	v_mov_b32_e32 v86, v2
	v_mov_b32_e32 v87, v2
	v_mov_b32_e32 v88, v2
	v_mov_b32_e32 v89, v2
	v_mov_b32_e32 v98, v2
	v_mov_b32_e32 v99, v2
	v_mov_b32_e32 v100, v2
	v_mov_b32_e32 v101, v2
	v_mov_b32_e32 v102, v2
	v_mov_b32_e32 v103, v2
	v_mov_b32_e32 v104, v2
	v_mov_b32_e32 v105, v2
	v_mov_b32_e32 v114, v2
	v_mov_b32_e32 v115, v2
	v_mov_b32_e32 v116, v2
	v_mov_b32_e32 v117, v2
	v_mov_b32_e32 v118, v2
	v_mov_b32_e32 v119, v2
	v_mov_b32_e32 v120, v2
	v_mov_b32_e32 v121, v2
	v_mov_b32_e32 v74, v2
	v_mov_b32_e32 v75, v2
	v_mov_b32_e32 v76, v2
	v_mov_b32_e32 v77, v2
	v_mov_b32_e32 v78, v2
	v_mov_b32_e32 v79, v2
	v_mov_b32_e32 v80, v2
	v_mov_b32_e32 v81, v2
	v_mov_b32_e32 v90, v2
	v_mov_b32_e32 v91, v2
	v_mov_b32_e32 v92, v2
	v_mov_b32_e32 v93, v2
	v_mov_b32_e32 v94, v2
	v_mov_b32_e32 v95, v2
	v_mov_b32_e32 v96, v2
	v_mov_b32_e32 v97, v2
	v_mov_b32_e32 v106, v2
	v_mov_b32_e32 v107, v2
	v_mov_b32_e32 v108, v2
	v_mov_b32_e32 v109, v2
	v_mov_b32_e32 v110, v2
	v_mov_b32_e32 v111, v2
	v_mov_b32_e32 v112, v2
	v_mov_b32_e32 v113, v2
	v_mov_b32_e32 v122, v2
	v_mov_b32_e32 v123, v2
	v_mov_b32_e32 v124, v2
	v_mov_b32_e32 v125, v2
	v_mov_b32_e32 v126, v2
	v_mov_b32_e32 v127, v2
	v_mov_b32_e32 v128, v2
	v_mov_b32_e32 v129, v2
	v_readfirstlane_b32 vcc_lo, v168
	s_lshr_b32 vcc_lo, vcc_lo, 6
	s_cmp_ge_u32 vcc_lo, 4
	s_cbranch_scc0 .Lgp_2
	s_setprio 1

; template <class Epi>
; __device__ __forceinline__ void gemm_phase(PG8_LAS unsigned char* lds, const Gemm g, const StaticOrder& S, const Epi& E) {
;     ...
;     const bool has_next = S.next(ui + 1, nxt);
;     const char* nA = has_next ? (const char*)g.A + (size_t)nxt.pm * tstep : cA; const char* nB = has_next ? (const char*)g.Bt + (size_t)nxt.pn * tstep : cB;
;     ...
; #pragma unroll
;     for (int a = 0; a < 2; ++a)
; #pragma unroll
;       for (int b = 0; b < 2; ++b)
; #pragma unroll
;         for (int m = 0; m < 4; ++m)
; #pragma unroll
;           for (int n = 0; n < 2; ++n) acc[a][b][m][n] = (f32x4){0.f, 0.f, 0.f, 0.f};
;     cur = nxt; cA = nA; cB = nB; ++ui;
.LBB0_1122:
	s_ashr_i32 s45, s44, 31
	v_cmp_lt_i64_e32 vcc, s[46:47], v[140:141]
	s_lshl_b64 s[46:47], s[44:45], 19
	s_add_u32 s46, s24, s46
	s_addc_u32 s47, s25, s47
	s_and_b64 s[48:49], vcc, exec
	s_cselect_b32 s45, s47, s9
	s_cselect_b32 s59, s46, s8
	s_ashr_i32 s43, s42, 31
	s_lshl_b64 s[48:49], s[42:43], 19
	v_readlane_b32 s43, v252, 58
	s_add_u32 s48, s43, s48
	v_readlane_b32 s43, v252, 59
	s_addc_u32 s49, s43, s49
	s_and_b64 s[50:51], vcc, exec
	s_cselect_b32 s43, s49, s11
	s_cselect_b32 s60, s48, s10
	s_add_u32 s8, s8, 0x40080
	s_addc_u32 s9, s9, 0
	s_add_u32 s61, s10, 0x100
	v_mov_b32_e32 v2, 0
	s_addc_u32 s62, s11, 0
	s_mov_b32 s63, -2
	v_mov_b32_e32 v3, v2
	v_mov_b32_e32 v4, v2
	v_mov_b32_e32 v5, v2
	v_mov_b32_e32 v6, v2
	v_mov_b32_e32 v7, v2
	v_mov_b32_e32 v8, v2
	v_mov_b32_e32 v9, v2
	v_mov_b32_e32 v18, v2
	v_mov_b32_e32 v19, v2
	v_mov_b32_e32 v20, v2
	v_mov_b32_e32 v21, v2
	v_mov_b32_e32 v22, v2
	v_mov_b32_e32 v23, v2
	v_mov_b32_e32 v24, v2
	v_mov_b32_e32 v25, v2
	v_mov_b32_e32 v34, v2
	v_mov_b32_e32 v35, v2
	v_mov_b32_e32 v36, v2
	v_mov_b32_e32 v37, v2
	v_mov_b32_e32 v38, v2
	v_mov_b32_e32 v39, v2
	v_mov_b32_e32 v40, v2
	v_mov_b32_e32 v41, v2
	v_mov_b32_e32 v50, v2
	v_mov_b32_e32 v51, v2
	v_mov_b32_e32 v52, v2
	v_mov_b32_e32 v53, v2
	v_mov_b32_e32 v54, v2
	v_mov_b32_e32 v55, v2
	v_mov_b32_e32 v56, v2
	v_mov_b32_e32 v57, v2
	v_mov_b32_e32 v10, v2
	v_mov_b32_e32 v11, v2
	v_mov_b32_e32 v12, v2
	v_mov_b32_e32 v13, v2
	v_mov_b32_e32 v14, v2
	v_mov_b32_e32 v15, v2
	v_mov_b32_e32 v16, v2
	v_mov_b32_e32 v17, v2
	v_mov_b32_e32 v26, v2
	v_mov_b32_e32 v27, v2
	v_mov_b32_e32 v28, v2
	v_mov_b32_e32 v29, v2
	v_mov_b32_e32 v30, v2
	v_mov_b32_e32 v31, v2
	v_mov_b32_e32 v32, v2
	v_mov_b32_e32 v33, v2
	v_mov_b32_e32 v42, v2
	v_mov_b32_e32 v43, v2
	v_mov_b32_e32 v44, v2
	v_mov_b32_e32 v45, v2
	v_mov_b32_e32 v46, v2
	v_mov_b32_e32 v47, v2
	v_mov_b32_e32 v48, v2
	v_mov_b32_e32 v49, v2
	v_mov_b32_e32 v58, v2
	v_mov_b32_e32 v59, v2
	v_mov_b32_e32 v60, v2
	v_mov_b32_e32 v61, v2
	v_mov_b32_e32 v62, v2
	v_mov_b32_e32 v63, v2
	v_mov_b32_e32 v64, v2
	v_mov_b32_e32 v65, v2
	v_mov_b32_e32 v66, v2
	v_mov_b32_e32 v67, v2
	v_mov_b32_e32 v68, v2
	v_mov_b32_e32 v69, v2
	v_mov_b32_e32 v70, v2
	v_mov_b32_e32 v71, v2
	v_mov_b32_e32 v72, v2
	v_mov_b32_e32 v73, v2
	v_mov_b32_e32 v82, v2
	v_mov_b32_e32 v83, v2
	v_mov_b32_e32 v84, v2
	v_mov_b32_e32 v85, v2
	v_mov_b32_e32 v86, v2
	v_mov_b32_e32 v87, v2
	v_mov_b32_e32 v88, v2
	v_mov_b32_e32 v89, v2
	v_mov_b32_e32 v98, v2
	v_mov_b32_e32 v99, v2
	v_mov_b32_e32 v100, v2
	v_mov_b32_e32 v101, v2
	v_mov_b32_e32 v102, v2
	v_mov_b32_e32 v103, v2
	v_mov_b32_e32 v104, v2
	v_mov_b32_e32 v105, v2
	v_mov_b32_e32 v114, v2
	v_mov_b32_e32 v115, v2
	v_mov_b32_e32 v116, v2
	v_mov_b32_e32 v117, v2
	v_mov_b32_e32 v118, v2
	v_mov_b32_e32 v119, v2
	v_mov_b32_e32 v120, v2
	v_mov_b32_e32 v121, v2
	v_mov_b32_e32 v74, v2
	v_mov_b32_e32 v75, v2
	v_mov_b32_e32 v76, v2
	v_mov_b32_e32 v77, v2
	v_mov_b32_e32 v78, v2
	v_mov_b32_e32 v79, v2
	v_mov_b32_e32 v80, v2
	v_mov_b32_e32 v81, v2
	v_mov_b32_e32 v90, v2
	v_mov_b32_e32 v91, v2
	v_mov_b32_e32 v92, v2
	v_mov_b32_e32 v93, v2
	v_mov_b32_e32 v94, v2
	v_mov_b32_e32 v95, v2
	v_mov_b32_e32 v96, v2
	v_mov_b32_e32 v97, v2
	v_mov_b32_e32 v106, v2
	v_mov_b32_e32 v107, v2
	v_mov_b32_e32 v108, v2
	v_mov_b32_e32 v109, v2
	v_mov_b32_e32 v110, v2
	v_mov_b32_e32 v111, v2
	v_mov_b32_e32 v112, v2
	v_mov_b32_e32 v113, v2
	v_mov_b32_e32 v122, v2
	v_mov_b32_e32 v123, v2
	v_mov_b32_e32 v124, v2
	v_mov_b32_e32 v125, v2
	v_mov_b32_e32 v126, v2
	v_mov_b32_e32 v127, v2
	v_mov_b32_e32 v128, v2
	v_mov_b32_e32 v129, v2
	v_readfirstlane_b32 vcc_lo, v168
	s_lshr_b32 vcc_lo, vcc_lo, 6
	s_cmp_ge_u32 vcc_lo, 4
	s_cbranch_scc0 .Lgp_3
	s_setprio 1

; template <class Epi>
; __device__ __forceinline__ void gemm_phase(PG8_LAS unsigned char* lds, const Gemm g, const StaticOrder& S, const Epi& E) {
;     ...
;     const bool has_next = S.next(ui + 1, nxt);
;     const char* nA = has_next ? (const char*)g.A + (size_t)nxt.pm * tstep : cA; const char* nB = has_next ? (const char*)g.Bt + (size_t)nxt.pn * tstep : cB;
;     ...
; #pragma unroll
;     for (int a = 0; a < 2; ++a)
; #pragma unroll
;       for (int b = 0; b < 2; ++b)
; #pragma unroll
;         for (int m = 0; m < 4; ++m)
; #pragma unroll
;           for (int n = 0; n < 2; ++n) acc[a][b][m][n] = (f32x4){0.f, 0.f, 0.f, 0.f};
;     cur = nxt; cA = nA; cB = nB; ++ui;
.LBB0_1229:
	s_ashr_i32 s9, s8, 31
	v_cmp_lt_i64_e32 vcc, s[10:11], v[136:137]
	s_lshl_b64 s[10:11], s[8:9], 19
	s_add_u32 s10, s24, s10
	s_addc_u32 s11, s25, s11
	s_and_b64 s[30:31], vcc, exec
	s_cselect_b32 s9, s11, s47
	s_cselect_b32 s43, s10, s46
	s_ashr_i32 s7, s6, 31
	s_lshl_b64 s[30:31], s[6:7], 19
	s_add_u32 s30, s22, s30
	s_addc_u32 s31, s23, s31
	s_and_b64 s[50:51], vcc, exec
	s_cselect_b32 s7, s31, s49
	s_cselect_b32 s45, s30, s48
	s_add_u32 s46, s46, 0x40080
	s_addc_u32 s47, s47, 0
	s_add_u32 s52, s48, 0x100
	v_mov_b32_e32 v2, 0
	s_addc_u32 s53, s49, 0
	s_mov_b32 s62, -2
	v_mov_b32_e32 v3, v2
	v_mov_b32_e32 v4, v2
	v_mov_b32_e32 v5, v2
	v_mov_b32_e32 v6, v2
	v_mov_b32_e32 v7, v2
	v_mov_b32_e32 v8, v2
	v_mov_b32_e32 v9, v2
	v_mov_b32_e32 v18, v2
	v_mov_b32_e32 v19, v2
	v_mov_b32_e32 v20, v2
	v_mov_b32_e32 v21, v2
	v_mov_b32_e32 v22, v2
	v_mov_b32_e32 v23, v2
	v_mov_b32_e32 v24, v2
	v_mov_b32_e32 v25, v2
	v_mov_b32_e32 v34, v2
	v_mov_b32_e32 v35, v2
	v_mov_b32_e32 v36, v2
	v_mov_b32_e32 v37, v2
	v_mov_b32_e32 v38, v2
	v_mov_b32_e32 v39, v2
	v_mov_b32_e32 v40, v2
	v_mov_b32_e32 v41, v2
	v_mov_b32_e32 v50, v2
	v_mov_b32_e32 v51, v2
	v_mov_b32_e32 v52, v2
	v_mov_b32_e32 v53, v2
	v_mov_b32_e32 v54, v2
	v_mov_b32_e32 v55, v2
	v_mov_b32_e32 v56, v2
	v_mov_b32_e32 v57, v2
	v_mov_b32_e32 v10, v2
	v_mov_b32_e32 v11, v2
	v_mov_b32_e32 v12, v2
	v_mov_b32_e32 v13, v2
	v_mov_b32_e32 v14, v2
	v_mov_b32_e32 v15, v2
	v_mov_b32_e32 v16, v2
	v_mov_b32_e32 v17, v2
	v_mov_b32_e32 v26, v2
	v_mov_b32_e32 v27, v2
	v_mov_b32_e32 v28, v2
	v_mov_b32_e32 v29, v2
	v_mov_b32_e32 v30, v2
	v_mov_b32_e32 v31, v2
	v_mov_b32_e32 v32, v2
	v_mov_b32_e32 v33, v2
	v_mov_b32_e32 v42, v2
	v_mov_b32_e32 v43, v2
	v_mov_b32_e32 v44, v2
	v_mov_b32_e32 v45, v2
	v_mov_b32_e32 v46, v2
	v_mov_b32_e32 v47, v2
	v_mov_b32_e32 v48, v2
	v_mov_b32_e32 v49, v2
	v_mov_b32_e32 v58, v2
	v_mov_b32_e32 v59, v2
	v_mov_b32_e32 v60, v2
	v_mov_b32_e32 v61, v2
	v_mov_b32_e32 v62, v2
	v_mov_b32_e32 v63, v2
	v_mov_b32_e32 v64, v2
	v_mov_b32_e32 v65, v2
	v_mov_b32_e32 v66, v2
	v_mov_b32_e32 v67, v2
	v_mov_b32_e32 v68, v2
	v_mov_b32_e32 v69, v2
	v_mov_b32_e32 v70, v2
	v_mov_b32_e32 v71, v2
	v_mov_b32_e32 v72, v2
	v_mov_b32_e32 v73, v2
	v_mov_b32_e32 v82, v2
	v_mov_b32_e32 v83, v2
	v_mov_b32_e32 v84, v2
	v_mov_b32_e32 v85, v2
	v_mov_b32_e32 v86, v2
	v_mov_b32_e32 v87, v2
	v_mov_b32_e32 v88, v2
	v_mov_b32_e32 v89, v2
	v_mov_b32_e32 v98, v2
	v_mov_b32_e32 v99, v2
	v_mov_b32_e32 v100, v2
	v_mov_b32_e32 v101, v2
	v_mov_b32_e32 v102, v2
	v_mov_b32_e32 v103, v2
	v_mov_b32_e32 v104, v2
	v_mov_b32_e32 v105, v2
	v_mov_b32_e32 v114, v2
	v_mov_b32_e32 v115, v2
	v_mov_b32_e32 v116, v2
	v_mov_b32_e32 v117, v2
	v_mov_b32_e32 v118, v2
	v_mov_b32_e32 v119, v2
	v_mov_b32_e32 v120, v2
	v_mov_b32_e32 v121, v2
	v_mov_b32_e32 v74, v2
	v_mov_b32_e32 v75, v2
	v_mov_b32_e32 v76, v2
	v_mov_b32_e32 v77, v2
	v_mov_b32_e32 v78, v2
	v_mov_b32_e32 v79, v2
	v_mov_b32_e32 v80, v2
	v_mov_b32_e32 v81, v2
	v_mov_b32_e32 v90, v2
	v_mov_b32_e32 v91, v2
	v_mov_b32_e32 v92, v2
	v_mov_b32_e32 v93, v2
	v_mov_b32_e32 v94, v2
	v_mov_b32_e32 v95, v2
	v_mov_b32_e32 v96, v2
	v_mov_b32_e32 v97, v2
	v_mov_b32_e32 v106, v2
	v_mov_b32_e32 v107, v2
	v_mov_b32_e32 v108, v2
	v_mov_b32_e32 v109, v2
	v_mov_b32_e32 v110, v2
	v_mov_b32_e32 v111, v2
	v_mov_b32_e32 v112, v2
	v_mov_b32_e32 v113, v2
	v_mov_b32_e32 v122, v2
	v_mov_b32_e32 v123, v2
	v_mov_b32_e32 v124, v2
	v_mov_b32_e32 v125, v2
	v_mov_b32_e32 v126, v2
	v_mov_b32_e32 v127, v2
	v_mov_b32_e32 v128, v2
	v_mov_b32_e32 v129, v2
	v_readfirstlane_b32 vcc_lo, v168
	s_lshr_b32 vcc_lo, vcc_lo, 6
	s_cmp_ge_u32 vcc_lo, 4
	s_cbranch_scc0 .Lgp_4
	s_setprio 1

; template <class Epi>
; __device__ __forceinline__ void gemm_phase(PG8_LAS unsigned char* lds, const Gemm g, const StaticOrder& S, const Epi& E) {
;     ...
; #pragma unroll
;     for (int a = 0; a < 2; ++a)
; #pragma unroll
;       for (int b = 0; b < 2; ++b)
; #pragma unroll
;         for (int m = 0; m < 4; ++m)
; #pragma unroll
;           for (int n = 0; n < 2; ++n) acc[a][b][m][n] = (f32x4){0.f, 0.f, 0.f, 0.f};
;     cur = nxt; cA = nA; cB = nB; ++ui;
.LBB0_1409:
	s_add_u32 s59, s46, 0x100
	v_mov_b32_e32 v2, 0
	s_addc_u32 s60, s47, 0
	s_mov_b32 s61, -2
	v_mov_b32_e32 v3, v2
	v_mov_b32_e32 v4, v2
	v_mov_b32_e32 v5, v2
	v_mov_b32_e32 v6, v2
	v_mov_b32_e32 v7, v2
	v_mov_b32_e32 v8, v2
	v_mov_b32_e32 v9, v2
	v_mov_b32_e32 v18, v2
	v_mov_b32_e32 v19, v2
	v_mov_b32_e32 v20, v2
	v_mov_b32_e32 v21, v2
	v_mov_b32_e32 v22, v2
	v_mov_b32_e32 v23, v2
	v_mov_b32_e32 v24, v2
	v_mov_b32_e32 v25, v2
	v_mov_b32_e32 v34, v2
	v_mov_b32_e32 v35, v2
	v_mov_b32_e32 v36, v2
	v_mov_b32_e32 v37, v2
	v_mov_b32_e32 v38, v2
	v_mov_b32_e32 v39, v2
	v_mov_b32_e32 v40, v2
	v_mov_b32_e32 v41, v2
	v_mov_b32_e32 v50, v2
	v_mov_b32_e32 v51, v2
	v_mov_b32_e32 v52, v2
	v_mov_b32_e32 v53, v2
	v_mov_b32_e32 v54, v2
	v_mov_b32_e32 v55, v2
	v_mov_b32_e32 v56, v2
	v_mov_b32_e32 v57, v2
	v_mov_b32_e32 v10, v2
	v_mov_b32_e32 v11, v2
	v_mov_b32_e32 v12, v2
	v_mov_b32_e32 v13, v2
	v_mov_b32_e32 v14, v2
	v_mov_b32_e32 v15, v2
	v_mov_b32_e32 v16, v2
	v_mov_b32_e32 v17, v2
	v_mov_b32_e32 v26, v2
	v_mov_b32_e32 v27, v2
	v_mov_b32_e32 v28, v2
	v_mov_b32_e32 v29, v2
	v_mov_b32_e32 v30, v2
	v_mov_b32_e32 v31, v2
	v_mov_b32_e32 v32, v2
	v_mov_b32_e32 v33, v2
	v_mov_b32_e32 v42, v2
	v_mov_b32_e32 v43, v2
	v_mov_b32_e32 v44, v2
	v_mov_b32_e32 v45, v2
	v_mov_b32_e32 v46, v2
	v_mov_b32_e32 v47, v2
	v_mov_b32_e32 v48, v2
	v_mov_b32_e32 v49, v2
	v_mov_b32_e32 v58, v2
	v_mov_b32_e32 v59, v2
	v_mov_b32_e32 v60, v2
	v_mov_b32_e32 v61, v2
	v_mov_b32_e32 v62, v2
	v_mov_b32_e32 v63, v2
	v_mov_b32_e32 v64, v2
	v_mov_b32_e32 v65, v2
	v_mov_b32_e32 v66, v2
	v_mov_b32_e32 v67, v2
	v_mov_b32_e32 v68, v2
	v_mov_b32_e32 v69, v2
	v_mov_b32_e32 v70, v2
	v_mov_b32_e32 v71, v2
	v_mov_b32_e32 v72, v2
	v_mov_b32_e32 v73, v2
	v_mov_b32_e32 v82, v2
	v_mov_b32_e32 v83, v2
	v_mov_b32_e32 v84, v2
	v_mov_b32_e32 v85, v2
	v_mov_b32_e32 v86, v2
	v_mov_b32_e32 v87, v2
	v_mov_b32_e32 v88, v2
	v_mov_b32_e32 v89, v2
	v_mov_b32_e32 v98, v2
	v_mov_b32_e32 v99, v2
	v_mov_b32_e32 v100, v2
	v_mov_b32_e32 v101, v2
	v_mov_b32_e32 v102, v2
	v_mov_b32_e32 v103, v2
	v_mov_b32_e32 v104, v2
	v_mov_b32_e32 v105, v2
	v_mov_b32_e32 v114, v2
	v_mov_b32_e32 v115, v2
	v_mov_b32_e32 v116, v2
	v_mov_b32_e32 v117, v2
	v_mov_b32_e32 v118, v2
	v_mov_b32_e32 v119, v2
	v_mov_b32_e32 v120, v2
	v_mov_b32_e32 v121, v2
	v_mov_b32_e32 v74, v2
	v_mov_b32_e32 v75, v2
	v_mov_b32_e32 v76, v2
	v_mov_b32_e32 v77, v2
	v_mov_b32_e32 v78, v2
	v_mov_b32_e32 v79, v2
	v_mov_b32_e32 v80, v2
	v_mov_b32_e32 v81, v2
	v_mov_b32_e32 v90, v2
	v_mov_b32_e32 v91, v2
	v_mov_b32_e32 v92, v2
	v_mov_b32_e32 v93, v2
	v_mov_b32_e32 v94, v2
	v_mov_b32_e32 v95, v2
	v_mov_b32_e32 v96, v2
	v_mov_b32_e32 v97, v2
	v_mov_b32_e32 v106, v2
	v_mov_b32_e32 v107, v2
	v_mov_b32_e32 v108, v2
	v_mov_b32_e32 v109, v2
	v_mov_b32_e32 v110, v2
	v_mov_b32_e32 v111, v2
	v_mov_b32_e32 v112, v2
	v_mov_b32_e32 v113, v2
	v_mov_b32_e32 v122, v2
	v_mov_b32_e32 v123, v2
	v_mov_b32_e32 v124, v2
	v_mov_b32_e32 v125, v2
	v_mov_b32_e32 v126, v2
	v_mov_b32_e32 v127, v2
	v_mov_b32_e32 v128, v2
	v_mov_b32_e32 v129, v2
	v_readfirstlane_b32 vcc_lo, v168
	s_lshr_b32 vcc_lo, vcc_lo, 6
	s_cmp_ge_u32 vcc_lo, 4
	s_cbranch_scc0 .Lgp_5
	s_setprio 1

; template <class Epi>
; __device__ __forceinline__ void gemm_phase(PG8_LAS unsigned char* lds, const Gemm g, const StaticOrder& S, const Epi& E) {
;     ...
;     const bool has_next = S.next(ui + 1, nxt);
;     const char* nA = has_next ? (const char*)g.A + (size_t)nxt.pm * tstep : cA; const char* nB = has_next ? (const char*)g.Bt + (size_t)nxt.pn * tstep : cB;
;     ...
; #pragma unroll
;     for (int a = 0; a < 2; ++a)
; #pragma unroll
;       for (int b = 0; b < 2; ++b)
; #pragma unroll
;         for (int m = 0; m < 4; ++m)
; #pragma unroll
;           for (int n = 0; n < 2; ++n) acc[a][b][m][n] = (f32x4){0.f, 0.f, 0.f, 0.f};
;     cur = nxt; cA = nA; cB = nB; ++ui;
.LBB0_1592:
	s_ashr_i32 s9, s8, 31
	v_cmp_lt_i64_e32 vcc, s[10:11], v[144:145]
	s_lshl_b64 s[10:11], s[8:9], 19
	s_add_u32 s10, s24, s10
	s_addc_u32 s11, s25, s11
	s_and_b64 s[12:13], vcc, exec
	s_cselect_b32 s9, s11, s45
	s_cselect_b32 s31, s10, s44
	s_ashr_i32 s7, s6, 31
	s_lshl_b64 s[12:13], s[6:7], 19
	s_add_u32 s12, s22, s12
	s_addc_u32 s13, s23, s13
	s_and_b64 s[48:49], vcc, exec
	s_cselect_b32 s7, s13, s47
	s_cselect_b32 s43, s12, s46
	s_add_u32 s44, s44, 0x40080
	s_addc_u32 s45, s45, 0
	s_add_u32 s56, s46, 0x100
	v_mov_b32_e32 v2, 0
	s_addc_u32 s57, s47, 0
	s_mov_b32 s58, -2
	v_mov_b32_e32 v3, v2
	v_mov_b32_e32 v4, v2
	v_mov_b32_e32 v5, v2
	v_mov_b32_e32 v6, v2
	v_mov_b32_e32 v7, v2
	v_mov_b32_e32 v8, v2
	v_mov_b32_e32 v9, v2
	v_mov_b32_e32 v18, v2
	v_mov_b32_e32 v19, v2
	v_mov_b32_e32 v20, v2
	v_mov_b32_e32 v21, v2
	v_mov_b32_e32 v22, v2
	v_mov_b32_e32 v23, v2
	v_mov_b32_e32 v24, v2
	v_mov_b32_e32 v25, v2
	v_mov_b32_e32 v34, v2
	v_mov_b32_e32 v35, v2
	v_mov_b32_e32 v36, v2
	v_mov_b32_e32 v37, v2
	v_mov_b32_e32 v38, v2
	v_mov_b32_e32 v39, v2
	v_mov_b32_e32 v40, v2
	v_mov_b32_e32 v41, v2
	v_mov_b32_e32 v50, v2
	v_mov_b32_e32 v51, v2
	v_mov_b32_e32 v52, v2
	v_mov_b32_e32 v53, v2
	v_mov_b32_e32 v54, v2
	v_mov_b32_e32 v55, v2
	v_mov_b32_e32 v56, v2
	v_mov_b32_e32 v57, v2
	v_mov_b32_e32 v10, v2
	v_mov_b32_e32 v11, v2
	v_mov_b32_e32 v12, v2
	v_mov_b32_e32 v13, v2
	v_mov_b32_e32 v14, v2
	v_mov_b32_e32 v15, v2
	v_mov_b32_e32 v16, v2
	v_mov_b32_e32 v17, v2
	v_mov_b32_e32 v26, v2
	v_mov_b32_e32 v27, v2
	v_mov_b32_e32 v28, v2
	v_mov_b32_e32 v29, v2
	v_mov_b32_e32 v30, v2
	v_mov_b32_e32 v31, v2
	v_mov_b32_e32 v32, v2
	v_mov_b32_e32 v33, v2
	v_mov_b32_e32 v42, v2
	v_mov_b32_e32 v43, v2
	v_mov_b32_e32 v44, v2
	v_mov_b32_e32 v45, v2
	v_mov_b32_e32 v46, v2
	v_mov_b32_e32 v47, v2
	v_mov_b32_e32 v48, v2
	v_mov_b32_e32 v49, v2
	v_mov_b32_e32 v58, v2
	v_mov_b32_e32 v59, v2
	v_mov_b32_e32 v60, v2
	v_mov_b32_e32 v61, v2
	v_mov_b32_e32 v62, v2
	v_mov_b32_e32 v63, v2
	v_mov_b32_e32 v64, v2
	v_mov_b32_e32 v65, v2
	v_mov_b32_e32 v66, v2
	v_mov_b32_e32 v67, v2
	v_mov_b32_e32 v68, v2
	v_mov_b32_e32 v69, v2
	v_mov_b32_e32 v70, v2
	v_mov_b32_e32 v71, v2
	v_mov_b32_e32 v72, v2
	v_mov_b32_e32 v73, v2
	v_mov_b32_e32 v82, v2
	v_mov_b32_e32 v83, v2
	v_mov_b32_e32 v84, v2
	v_mov_b32_e32 v85, v2
	v_mov_b32_e32 v86, v2
	v_mov_b32_e32 v87, v2
	v_mov_b32_e32 v88, v2
	v_mov_b32_e32 v89, v2
	v_mov_b32_e32 v98, v2
	v_mov_b32_e32 v99, v2
	v_mov_b32_e32 v100, v2
	v_mov_b32_e32 v101, v2
	v_mov_b32_e32 v102, v2
	v_mov_b32_e32 v103, v2
	v_mov_b32_e32 v104, v2
	v_mov_b32_e32 v105, v2
	v_mov_b32_e32 v114, v2
	v_mov_b32_e32 v115, v2
	v_mov_b32_e32 v116, v2
	v_mov_b32_e32 v117, v2
	v_mov_b32_e32 v118, v2
	v_mov_b32_e32 v119, v2
	v_mov_b32_e32 v120, v2
	v_mov_b32_e32 v121, v2
	v_mov_b32_e32 v74, v2
	v_mov_b32_e32 v75, v2
	v_mov_b32_e32 v76, v2
	v_mov_b32_e32 v77, v2
	v_mov_b32_e32 v78, v2
	v_mov_b32_e32 v79, v2
	v_mov_b32_e32 v80, v2
	v_mov_b32_e32 v81, v2
	v_mov_b32_e32 v90, v2
	v_mov_b32_e32 v91, v2
	v_mov_b32_e32 v92, v2
	v_mov_b32_e32 v93, v2
	v_mov_b32_e32 v94, v2
	v_mov_b32_e32 v95, v2
	v_mov_b32_e32 v96, v2
	v_mov_b32_e32 v97, v2
	v_mov_b32_e32 v106, v2
	v_mov_b32_e32 v107, v2
	v_mov_b32_e32 v108, v2
	v_mov_b32_e32 v109, v2
	v_mov_b32_e32 v110, v2
	v_mov_b32_e32 v111, v2
	v_mov_b32_e32 v112, v2
	v_mov_b32_e32 v113, v2
	v_mov_b32_e32 v122, v2
	v_mov_b32_e32 v123, v2
	v_mov_b32_e32 v124, v2
	v_mov_b32_e32 v125, v2
	v_mov_b32_e32 v126, v2
	v_mov_b32_e32 v127, v2
	v_mov_b32_e32 v128, v2
	v_mov_b32_e32 v129, v2
	v_readfirstlane_b32 vcc_lo, v168
	s_lshr_b32 vcc_lo, vcc_lo, 6
	s_cmp_ge_u32 vcc_lo, 4
	s_cbranch_scc0 .Lgp_6
	s_setprio 1
